# scan pass 2: packed f32 FMAs on SGPR pairs (2 k-rows per instruction), on top of v17
# baseline (speedup 1.0000x reference)
; __device__ __forceinline__ void scan_pass2(const Ctx&, unsigned char* ws) { const Ctx c = mk_ctx();
;     ...
;         for (int cc = 0; cc < NCH - 1; ++cc) { float* P = PL + (((size_t)chain * NCH + cc) * 2) * 4096; float* L = P + 4096 + i * 64;
;             float a0 = L[lane], a1 = 0.f, a2 = 0.f, a3 = 0.f;
; #pragma unroll
;             for (int k = 0; k < 64; k += 4) { a0 += __shfl(s, k) * P[k * 64 + lane]; a1 += __shfl(s, k + 1) * P[(k + 1) * 64 + lane]; a2 += __shfl(s, k + 2) * P[(k + 2) * 64 + lane]; a3 += __shfl(s, k + 3) * P[(k + 3) * 64 + lane]; }
;             s = (a0 + a1) + (a2 + a3); L[lane] = s; }
.LBB0_2032:
	s_waitcnt vmcnt(1)
	v_mov_b32_e32 v14, v12
	v_mov_b32_e32 v15, 0
	v_mov_b32_e32 v144, 0
	v_mov_b32_e32 v145, 0
	v_lshl_add_u64 v[168:169], v[6:7], 0, s[0:1]
	global_load_dword v13, v[168:169], off
	v_readlane_b32 s6, v159, 0
	v_readlane_b32 s7, v159, 1
	v_readlane_b32 vcc_lo, v159, 2
	v_readlane_b32 vcc_hi, v159, 3
	global_load_dword v80, v[160:161], off
	global_load_dword v81, v[160:161], off offset:256
	global_load_dword v82, v[160:161], off offset:512
	global_load_dword v83, v[160:161], off offset:768
	v_pk_fma_f32 v[14:15], s[6:7], v[16:17], v[14:15]
	v_pk_fma_f32 v[144:145], vcc, v[18:19], v[144:145]
	v_readlane_b32 s6, v159, 4
	v_readlane_b32 s7, v159, 5
	v_readlane_b32 vcc_lo, v159, 6
	v_readlane_b32 vcc_hi, v159, 7
	global_load_dword v84, v[160:161], off offset:1024
	global_load_dword v85, v[160:161], off offset:1280
	global_load_dword v86, v[160:161], off offset:1536
	global_load_dword v87, v[160:161], off offset:1792
	v_pk_fma_f32 v[14:15], s[6:7], v[20:21], v[14:15]
	v_pk_fma_f32 v[144:145], vcc, v[22:23], v[144:145]
	v_readlane_b32 s6, v159, 8
	v_readlane_b32 s7, v159, 9
	v_readlane_b32 vcc_lo, v159, 10
	v_readlane_b32 vcc_hi, v159, 11
	global_load_dword v88, v[160:161], off offset:2048
	global_load_dword v89, v[160:161], off offset:2304
	global_load_dword v90, v[160:161], off offset:2560
	global_load_dword v91, v[160:161], off offset:2816
	v_pk_fma_f32 v[14:15], s[6:7], v[24:25], v[14:15]
	v_pk_fma_f32 v[144:145], vcc, v[26:27], v[144:145]
	v_readlane_b32 s6, v159, 12
	v_readlane_b32 s7, v159, 13
	v_readlane_b32 vcc_lo, v159, 14
	v_readlane_b32 vcc_hi, v159, 15
	global_load_dword v92, v[160:161], off offset:3072
	global_load_dword v93, v[160:161], off offset:3328
	global_load_dword v94, v[160:161], off offset:3584
	global_load_dword v95, v[160:161], off offset:3840
	v_pk_fma_f32 v[14:15], s[6:7], v[28:29], v[14:15]
	v_pk_fma_f32 v[144:145], vcc, v[30:31], v[144:145]
	v_readlane_b32 s6, v159, 16
	v_readlane_b32 s7, v159, 17
	v_readlane_b32 vcc_lo, v159, 18
	v_readlane_b32 vcc_hi, v159, 19
	global_load_dword v96, v[162:163], off
	global_load_dword v97, v[162:163], off offset:256
	global_load_dword v98, v[162:163], off offset:512
	global_load_dword v99, v[162:163], off offset:768
	v_pk_fma_f32 v[14:15], s[6:7], v[32:33], v[14:15]
	v_pk_fma_f32 v[144:145], vcc, v[34:35], v[144:145]
	v_readlane_b32 s6, v159, 20
	v_readlane_b32 s7, v159, 21
	v_readlane_b32 vcc_lo, v159, 22
	v_readlane_b32 vcc_hi, v159, 23
	global_load_dword v100, v[162:163], off offset:1024
	global_load_dword v101, v[162:163], off offset:1280
	global_load_dword v102, v[162:163], off offset:1536
	global_load_dword v103, v[162:163], off offset:1792
	v_pk_fma_f32 v[14:15], s[6:7], v[36:37], v[14:15]
	v_pk_fma_f32 v[144:145], vcc, v[38:39], v[144:145]
	v_readlane_b32 s6, v159, 24
	v_readlane_b32 s7, v159, 25
	v_readlane_b32 vcc_lo, v159, 26
	v_readlane_b32 vcc_hi, v159, 27
	global_load_dword v104, v[162:163], off offset:2048
	global_load_dword v105, v[162:163], off offset:2304
	global_load_dword v106, v[162:163], off offset:2560
	global_load_dword v107, v[162:163], off offset:2816
	v_pk_fma_f32 v[14:15], s[6:7], v[40:41], v[14:15]
	v_pk_fma_f32 v[144:145], vcc, v[42:43], v[144:145]
	v_readlane_b32 s6, v159, 28
	v_readlane_b32 s7, v159, 29
	v_readlane_b32 vcc_lo, v159, 30
	v_readlane_b32 vcc_hi, v159, 31
	global_load_dword v108, v[162:163], off offset:3072
	global_load_dword v109, v[162:163], off offset:3328
	global_load_dword v110, v[162:163], off offset:3584
	global_load_dword v111, v[162:163], off offset:3840
	v_pk_fma_f32 v[14:15], s[6:7], v[44:45], v[14:15]
	v_pk_fma_f32 v[144:145], vcc, v[46:47], v[144:145]
	v_readlane_b32 s6, v159, 32
	v_readlane_b32 s7, v159, 33
	v_readlane_b32 vcc_lo, v159, 34
	v_readlane_b32 vcc_hi, v159, 35
	global_load_dword v112, v[164:165], off
	global_load_dword v113, v[164:165], off offset:256
	global_load_dword v114, v[164:165], off offset:512
	global_load_dword v115, v[164:165], off offset:768
	v_pk_fma_f32 v[14:15], s[6:7], v[48:49], v[14:15]
	v_pk_fma_f32 v[144:145], vcc, v[50:51], v[144:145]
	v_readlane_b32 s6, v159, 36
	v_readlane_b32 s7, v159, 37
	v_readlane_b32 vcc_lo, v159, 38
	v_readlane_b32 vcc_hi, v159, 39
	global_load_dword v116, v[164:165], off offset:1024
	global_load_dword v117, v[164:165], off offset:1280
	global_load_dword v118, v[164:165], off offset:1536
	global_load_dword v119, v[164:165], off offset:1792
	v_pk_fma_f32 v[14:15], s[6:7], v[52:53], v[14:15]
	v_pk_fma_f32 v[144:145], vcc, v[54:55], v[144:145]
	v_readlane_b32 s6, v159, 40
	v_readlane_b32 s7, v159, 41
	v_readlane_b32 vcc_lo, v159, 42
	v_readlane_b32 vcc_hi, v159, 43
	global_load_dword v120, v[164:165], off offset:2048
	global_load_dword v121, v[164:165], off offset:2304
	global_load_dword v122, v[164:165], off offset:2560
	global_load_dword v123, v[164:165], off offset:2816
	v_pk_fma_f32 v[14:15], s[6:7], v[56:57], v[14:15]
	v_pk_fma_f32 v[144:145], vcc, v[58:59], v[144:145]
	v_readlane_b32 s6, v159, 44
	v_readlane_b32 s7, v159, 45
	v_readlane_b32 vcc_lo, v159, 46
	v_readlane_b32 vcc_hi, v159, 47
	global_load_dword v124, v[164:165], off offset:3072
	global_load_dword v125, v[164:165], off offset:3328
	global_load_dword v126, v[164:165], off offset:3584
	global_load_dword v127, v[164:165], off offset:3840
	v_pk_fma_f32 v[14:15], s[6:7], v[60:61], v[14:15]
	v_pk_fma_f32 v[144:145], vcc, v[62:63], v[144:145]
	v_readlane_b32 s6, v159, 48
	v_readlane_b32 s7, v159, 49
	v_readlane_b32 vcc_lo, v159, 50
	v_readlane_b32 vcc_hi, v159, 51
	global_load_dword v128, v[166:167], off
	global_load_dword v129, v[166:167], off offset:256
; __device__ __forceinline__ void scan_pass2(const Ctx&, unsigned char* ws) { const Ctx c = mk_ctx();
;     ...
;         for (int cc = 0; cc < NCH - 1; ++cc) { float* P = PL + (((size_t)chain * NCH + cc) * 2) * 4096; float* L = P + 4096 + i * 64;
;             float a0 = L[lane], a1 = 0.f, a2 = 0.f, a3 = 0.f;
; #pragma unroll
;             for (int k = 0; k < 64; k += 4) { a0 += __shfl(s, k) * P[k * 64 + lane]; a1 += __shfl(s, k + 1) * P[(k + 1) * 64 + lane]; a2 += __shfl(s, k + 2) * P[(k + 2) * 64 + lane]; a3 += __shfl(s, k + 3) * P[(k + 3) * 64 + lane]; }
;             s = (a0 + a1) + (a2 + a3); L[lane] = s; }
	global_load_dword v130, v[166:167], off offset:512
	global_load_dword v131, v[166:167], off offset:768
	v_pk_fma_f32 v[14:15], s[6:7], v[64:65], v[14:15]
	v_pk_fma_f32 v[144:145], vcc, v[66:67], v[144:145]
	v_readlane_b32 s6, v159, 52
	v_readlane_b32 s7, v159, 53
	v_readlane_b32 vcc_lo, v159, 54
	v_readlane_b32 vcc_hi, v159, 55
	global_load_dword v132, v[166:167], off offset:1024
	global_load_dword v133, v[166:167], off offset:1280
	global_load_dword v134, v[166:167], off offset:1536
	global_load_dword v135, v[166:167], off offset:1792
	v_pk_fma_f32 v[14:15], s[6:7], v[68:69], v[14:15]
	v_pk_fma_f32 v[144:145], vcc, v[70:71], v[144:145]
	v_readlane_b32 s6, v159, 56
	v_readlane_b32 s7, v159, 57
	v_readlane_b32 vcc_lo, v159, 58
	v_readlane_b32 vcc_hi, v159, 59
	global_load_dword v136, v[166:167], off offset:2048
	global_load_dword v137, v[166:167], off offset:2304
	global_load_dword v138, v[166:167], off offset:2560
	global_load_dword v139, v[166:167], off offset:2816
	v_pk_fma_f32 v[14:15], s[6:7], v[72:73], v[14:15]
	v_pk_fma_f32 v[144:145], vcc, v[74:75], v[144:145]
	v_readlane_b32 s6, v159, 60
	v_readlane_b32 s7, v159, 61
	v_readlane_b32 vcc_lo, v159, 62
	v_readlane_b32 vcc_hi, v159, 63
	global_load_dword v140, v[166:167], off offset:3072
	global_load_dword v141, v[166:167], off offset:3328
	global_load_dword v142, v[166:167], off offset:3584
	global_load_dword v143, v[166:167], off offset:3840
	v_pk_fma_f32 v[14:15], s[6:7], v[76:77], v[14:15]
	v_pk_fma_f32 v[144:145], vcc, v[78:79], v[144:145]
	v_add_f32_e32 v14, v14, v15
	v_add_f32_e32 v144, v144, v145
	v_add_u32_e32 v170, 1, v170
	v_add_f32_e32 v159, v144, v14
	v_readfirstlane_b32 s6, v170
	global_store_dword v[6:7], v159, off
	v_mov_b32_e32 v6, v168
	v_mov_b32_e32 v7, v169
	v_lshl_add_u64 v[160:161], v[160:161], 0, s[0:1]
	v_lshl_add_u64 v[162:163], v[162:163], 0, s[0:1]
	v_lshl_add_u64 v[164:165], v[164:165], 0, s[0:1]
	v_lshl_add_u64 v[166:167], v[166:167], 0, s[0:1]
	s_cmp_eq_u32 s6, 63
	s_cbranch_scc1 .Ls2_done
	s_waitcnt vmcnt(1)
	v_mov_b32_e32 v14, v13
	v_mov_b32_e32 v15, 0
	v_mov_b32_e32 v144, 0
	v_mov_b32_e32 v145, 0
	v_lshl_add_u64 v[168:169], v[6:7], 0, s[0:1]
	global_load_dword v12, v[168:169], off
	v_readlane_b32 s6, v159, 0
	v_readlane_b32 s7, v159, 1
	v_readlane_b32 vcc_lo, v159, 2
	v_readlane_b32 vcc_hi, v159, 3
	global_load_dword v16, v[160:161], off
	global_load_dword v17, v[160:161], off offset:256
	global_load_dword v18, v[160:161], off offset:512
	global_load_dword v19, v[160:161], off offset:768
	v_pk_fma_f32 v[14:15], s[6:7], v[80:81], v[14:15]
	v_pk_fma_f32 v[144:145], vcc, v[82:83], v[144:145]
	v_readlane_b32 s6, v159, 4
	v_readlane_b32 s7, v159, 5
	v_readlane_b32 vcc_lo, v159, 6
	v_readlane_b32 vcc_hi, v159, 7
	global_load_dword v20, v[160:161], off offset:1024
	global_load_dword v21, v[160:161], off offset:1280
	global_load_dword v22, v[160:161], off offset:1536
	global_load_dword v23, v[160:161], off offset:1792
	v_pk_fma_f32 v[14:15], s[6:7], v[84:85], v[14:15]
	v_pk_fma_f32 v[144:145], vcc, v[86:87], v[144:145]
	v_readlane_b32 s6, v159, 8
	v_readlane_b32 s7, v159, 9
	v_readlane_b32 vcc_lo, v159, 10
	v_readlane_b32 vcc_hi, v159, 11
	global_load_dword v24, v[160:161], off offset:2048
	global_load_dword v25, v[160:161], off offset:2304
	global_load_dword v26, v[160:161], off offset:2560
	global_load_dword v27, v[160:161], off offset:2816
	v_pk_fma_f32 v[14:15], s[6:7], v[88:89], v[14:15]
	v_pk_fma_f32 v[144:145], vcc, v[90:91], v[144:145]
	v_readlane_b32 s6, v159, 12
	v_readlane_b32 s7, v159, 13
	v_readlane_b32 vcc_lo, v159, 14
	v_readlane_b32 vcc_hi, v159, 15
	global_load_dword v28, v[160:161], off offset:3072
	global_load_dword v29, v[160:161], off offset:3328
	global_load_dword v30, v[160:161], off offset:3584
	global_load_dword v31, v[160:161], off offset:3840
	v_pk_fma_f32 v[14:15], s[6:7], v[92:93], v[14:15]
	v_pk_fma_f32 v[144:145], vcc, v[94:95], v[144:145]
	v_readlane_b32 s6, v159, 16
	v_readlane_b32 s7, v159, 17
	v_readlane_b32 vcc_lo, v159, 18
	v_readlane_b32 vcc_hi, v159, 19
	global_load_dword v32, v[162:163], off
	global_load_dword v33, v[162:163], off offset:256
	global_load_dword v34, v[162:163], off offset:512
	global_load_dword v35, v[162:163], off offset:768
	v_pk_fma_f32 v[14:15], s[6:7], v[96:97], v[14:15]
	v_pk_fma_f32 v[144:145], vcc, v[98:99], v[144:145]
	v_readlane_b32 s6, v159, 20
	v_readlane_b32 s7, v159, 21
	v_readlane_b32 vcc_lo, v159, 22
	v_readlane_b32 vcc_hi, v159, 23
	global_load_dword v36, v[162:163], off offset:1024
	global_load_dword v37, v[162:163], off offset:1280
	global_load_dword v38, v[162:163], off offset:1536
	global_load_dword v39, v[162:163], off offset:1792
	v_pk_fma_f32 v[14:15], s[6:7], v[100:101], v[14:15]
	v_pk_fma_f32 v[144:145], vcc, v[102:103], v[144:145]
	v_readlane_b32 s6, v159, 24
; __device__ __forceinline__ void scan_pass2(const Ctx&, unsigned char* ws) { const Ctx c = mk_ctx();
;     ...
;         for (int cc = 0; cc < NCH - 1; ++cc) { float* P = PL + (((size_t)chain * NCH + cc) * 2) * 4096; float* L = P + 4096 + i * 64;
;             float a0 = L[lane], a1 = 0.f, a2 = 0.f, a3 = 0.f;
; #pragma unroll
;             for (int k = 0; k < 64; k += 4) { a0 += __shfl(s, k) * P[k * 64 + lane]; a1 += __shfl(s, k + 1) * P[(k + 1) * 64 + lane]; a2 += __shfl(s, k + 2) * P[(k + 2) * 64 + lane]; a3 += __shfl(s, k + 3) * P[(k + 3) * 64 + lane]; }
;             s = (a0 + a1) + (a2 + a3); L[lane] = s; }
	v_readlane_b32 s7, v159, 25
	v_readlane_b32 vcc_lo, v159, 26
	v_readlane_b32 vcc_hi, v159, 27
	global_load_dword v40, v[162:163], off offset:2048
	global_load_dword v41, v[162:163], off offset:2304
	global_load_dword v42, v[162:163], off offset:2560
	global_load_dword v43, v[162:163], off offset:2816
	v_pk_fma_f32 v[14:15], s[6:7], v[104:105], v[14:15]
	v_pk_fma_f32 v[144:145], vcc, v[106:107], v[144:145]
	v_readlane_b32 s6, v159, 28
	v_readlane_b32 s7, v159, 29
	v_readlane_b32 vcc_lo, v159, 30
	v_readlane_b32 vcc_hi, v159, 31
	global_load_dword v44, v[162:163], off offset:3072
	global_load_dword v45, v[162:163], off offset:3328
	global_load_dword v46, v[162:163], off offset:3584
	global_load_dword v47, v[162:163], off offset:3840
	v_pk_fma_f32 v[14:15], s[6:7], v[108:109], v[14:15]
	v_pk_fma_f32 v[144:145], vcc, v[110:111], v[144:145]
	v_readlane_b32 s6, v159, 32
	v_readlane_b32 s7, v159, 33
	v_readlane_b32 vcc_lo, v159, 34
	v_readlane_b32 vcc_hi, v159, 35
	global_load_dword v48, v[164:165], off
	global_load_dword v49, v[164:165], off offset:256
	global_load_dword v50, v[164:165], off offset:512
	global_load_dword v51, v[164:165], off offset:768
	v_pk_fma_f32 v[14:15], s[6:7], v[112:113], v[14:15]
	v_pk_fma_f32 v[144:145], vcc, v[114:115], v[144:145]
	v_readlane_b32 s6, v159, 36
	v_readlane_b32 s7, v159, 37
	v_readlane_b32 vcc_lo, v159, 38
	v_readlane_b32 vcc_hi, v159, 39
	global_load_dword v52, v[164:165], off offset:1024
	global_load_dword v53, v[164:165], off offset:1280
	global_load_dword v54, v[164:165], off offset:1536
	global_load_dword v55, v[164:165], off offset:1792
	v_pk_fma_f32 v[14:15], s[6:7], v[116:117], v[14:15]
	v_pk_fma_f32 v[144:145], vcc, v[118:119], v[144:145]
	v_readlane_b32 s6, v159, 40
	v_readlane_b32 s7, v159, 41
	v_readlane_b32 vcc_lo, v159, 42
	v_readlane_b32 vcc_hi, v159, 43
	global_load_dword v56, v[164:165], off offset:2048
	global_load_dword v57, v[164:165], off offset:2304
	global_load_dword v58, v[164:165], off offset:2560
	global_load_dword v59, v[164:165], off offset:2816
	v_pk_fma_f32 v[14:15], s[6:7], v[120:121], v[14:15]
	v_pk_fma_f32 v[144:145], vcc, v[122:123], v[144:145]
	v_readlane_b32 s6, v159, 44
	v_readlane_b32 s7, v159, 45
	v_readlane_b32 vcc_lo, v159, 46
	v_readlane_b32 vcc_hi, v159, 47
	global_load_dword v60, v[164:165], off offset:3072
	global_load_dword v61, v[164:165], off offset:3328
	global_load_dword v62, v[164:165], off offset:3584
	global_load_dword v63, v[164:165], off offset:3840
	v_pk_fma_f32 v[14:15], s[6:7], v[124:125], v[14:15]
	v_pk_fma_f32 v[144:145], vcc, v[126:127], v[144:145]
	v_readlane_b32 s6, v159, 48
	v_readlane_b32 s7, v159, 49
	v_readlane_b32 vcc_lo, v159, 50
	v_readlane_b32 vcc_hi, v159, 51
	global_load_dword v64, v[166:167], off
	global_load_dword v65, v[166:167], off offset:256
	global_load_dword v66, v[166:167], off offset:512
	global_load_dword v67, v[166:167], off offset:768
	v_pk_fma_f32 v[14:15], s[6:7], v[128:129], v[14:15]
	v_pk_fma_f32 v[144:145], vcc, v[130:131], v[144:145]
	v_readlane_b32 s6, v159, 52
	v_readlane_b32 s7, v159, 53
	v_readlane_b32 vcc_lo, v159, 54
	v_readlane_b32 vcc_hi, v159, 55
	global_load_dword v68, v[166:167], off offset:1024
	global_load_dword v69, v[166:167], off offset:1280
	global_load_dword v70, v[166:167], off offset:1536
	global_load_dword v71, v[166:167], off offset:1792
	v_pk_fma_f32 v[14:15], s[6:7], v[132:133], v[14:15]
	v_pk_fma_f32 v[144:145], vcc, v[134:135], v[144:145]
	v_readlane_b32 s6, v159, 56
	v_readlane_b32 s7, v159, 57
	v_readlane_b32 vcc_lo, v159, 58
	v_readlane_b32 vcc_hi, v159, 59
	global_load_dword v72, v[166:167], off offset:2048
	global_load_dword v73, v[166:167], off offset:2304
	global_load_dword v74, v[166:167], off offset:2560
	global_load_dword v75, v[166:167], off offset:2816
	v_pk_fma_f32 v[14:15], s[6:7], v[136:137], v[14:15]
	v_pk_fma_f32 v[144:145], vcc, v[138:139], v[144:145]
	v_readlane_b32 s6, v159, 60
	v_readlane_b32 s7, v159, 61
	v_readlane_b32 vcc_lo, v159, 62
	v_readlane_b32 vcc_hi, v159, 63
	global_load_dword v76, v[166:167], off offset:3072
	global_load_dword v77, v[166:167], off offset:3328
	global_load_dword v78, v[166:167], off offset:3584
	global_load_dword v79, v[166:167], off offset:3840
	v_pk_fma_f32 v[14:15], s[6:7], v[140:141], v[14:15]
	v_pk_fma_f32 v[144:145], vcc, v[142:143], v[144:145]
	v_add_f32_e32 v14, v14, v15
	v_add_f32_e32 v144, v144, v145
	v_add_u32_e32 v170, 1, v170
	v_add_f32_e32 v159, v144, v14
	v_readfirstlane_b32 s6, v170
	global_store_dword v[6:7], v159, off
	v_mov_b32_e32 v6, v168
	v_mov_b32_e32 v7, v169
	v_lshl_add_u64 v[160:161], v[160:161], 0, s[0:1]
	v_lshl_add_u64 v[162:163], v[162:163], 0, s[0:1]
	v_lshl_add_u64 v[164:165], v[164:165], 0, s[0:1]
	v_lshl_add_u64 v[166:167], v[166:167], 0, s[0:1]
	s_cmp_eq_u32 s6, 63
	s_cbranch_scc1 .Ls2_done
	s_branch .LBB0_2032
